# prep weight-transpose tiles: all eight row loads of a tile issued together; ssdout reductions via DPP
# speedup vs baseline: 1.0641x; 1.0027x over previous
.LBB0_35:
	s_mov_b32 s44, 0
	s_add_i32 s2, s44, s76
	s_waitcnt vmcnt(0)
	v_mbcnt_lo_u32_b32 v0, -1, 0
	v_mbcnt_hi_u32_b32 v0, -1, v0
	s_add_i32 s18, s44, s69
	v_lshl_add_u32 v176, s2, 6, v0
	s_add_i32 s82, s44, s72
	v_readfirstlane_b32 s2, v176
	s_ashr_i32 s6, s2, 6
	v_readlane_b32 s4, v254, 11
	s_cmp_gt_u32 s4, 16
	s_cselect_b64 s[2:3], -1, 0
	s_cmp_lt_u32 s4, 17
	s_cselect_b64 s[10:11], -1, 0
	s_and_b64 s[4:5], s[10:11], exec
	s_mov_b32 s4, 0x12000
	s_cselect_b32 s4, s4, 0x10000
	s_lshl_b32 s5, s82, 3
	s_abs_i32 s7, s5
	v_cvt_f32_u32_e32 v1, s7
	s_mov_b32 s14, s18
	v_writelane_b32 v254, s14, 41
	s_lshl_b32 s13, s18, 3
	v_rcp_iflag_f32_e32 v1, v1
	v_writelane_b32 v254, s15, 42
	s_add_i32 s6, s6, s13
	s_sub_i32 s13, 0, s7
	v_mul_f32_e32 v1, 0x4f7ffffe, v1
	v_cvt_u32_f32_e32 v1, v1
	s_add_i32 s12, s4, s5
	s_add_i32 s12, s12, -1
	s_xor_b32 s5, s12, s5
	v_readfirstlane_b32 s14, v1
	s_mul_i32 s13, s13, s14
	s_mul_hi_u32 s13, s14, s13
	s_abs_i32 s12, s12
	s_add_i32 s14, s14, s13
	s_mul_hi_u32 s13, s12, s14
	s_mul_i32 s14, s13, s7
	s_sub_i32 s12, s12, s14
	s_ashr_i32 s5, s5, 31
	s_add_i32 s14, s13, 1
	s_sub_i32 s15, s12, s7
	s_cmp_ge_u32 s12, s7
	s_cselect_b32 s13, s14, s13
	s_cselect_b32 s12, s15, s12
	s_add_i32 s14, s13, 1
	s_cmp_ge_u32 s12, s7
	s_cselect_b32 s7, s14, s13
	s_xor_b32 s7, s7, s5
	s_sub_i32 s5, s7, s5
	s_mul_i32 s56, s5, s6
	s_add_i32 s5, s56, s5
	s_min_i32 s57, s5, s4
	s_cmp_ge_i32 s56, s57
	s_mov_b32 s54, 0x800000
	s_cbranch_scc1 .LBB0_134
	v_readlane_b32 s28, v254, 11
	s_cmp_lg_u32 s28, 21
	s_cselect_b64 s[6:7], -1, 0
	s_cmp_eq_u32 s28, 21
	s_cselect_b64 s[12:13], -1, 0
	s_cmp_eq_u32 s28, 17
	s_cselect_b64 s[14:15], -1, 0
	s_lshl_b64 s[4:5], s[44:45], 3
	s_add_u32 s22, s70, s4
	v_readlane_b32 s24, v253, 62
	s_addc_u32 s23, s71, s5
	v_readlane_b32 s26, v254, 0
	v_readlane_b32 s27, v254, 1
	s_add_u32 s4, s26, s44
	s_addc_u32 s5, s27, 0
	s_lshl_b64 s[18:19], s[44:45], 2
	v_readlane_b32 s25, v253, 63
	s_add_u32 s58, s24, s18
	s_addc_u32 s59, s25, s19
	s_cmp_eq_u32 s28, 10
	s_cselect_b64 s[18:19], -1, 0
	s_and_b64 s[20:21], s[18:19], exec
	s_movk_i32 s20, 0x400
	s_cselect_b32 s60, s20, 0x1000
	s_cselect_b32 s61, 0, 0xc00
	s_or_b64 s[12:13], s[18:19], s[12:13]
	s_and_b64 s[18:19], s[12:13], exec
	s_cselect_b32 s18, 64, 48
	s_add_u32 s18, s22, s18
	s_addc_u32 s19, s23, 0
	s_load_dwordx2 s[18:19], s[18:19], 0x0
	s_and_b64 s[10:11], s[10:11], exec
	s_cselect_b32 s20, 0, 0x1000
	v_and_b32_e32 v34, 63, v0
	v_lshlrev_b32_e32 v192, 5, v34
	s_waitcnt lgkmcnt(0)
	s_add_u32 s10, s18, s20
	s_addc_u32 s11, s19, 0
	s_and_b64 s[12:13], s[12:13], exec
	s_cselect_b32 s12, 0x48, 56
	s_add_u32 s12, s22, s12
	s_addc_u32 s13, s23, 0
	s_load_dwordx2 s[12:13], s[12:13], 0x0
	v_xor_b32_e32 v32, 1, v229
	v_cmp_lt_i32_e32 vcc, v32, v231
	v_mov_b32_e32 v33, v193
	v_mov_b32_e32 v62, 0
	s_waitcnt lgkmcnt(0)
	s_add_u32 s12, s12, s20
	s_addc_u32 s13, s13, 0
	global_load_dwordx4 v[0:3], v192, s[10:11] offset:16
	global_load_dwordx4 v[4:7], v192, s[10:11]
	global_load_dwordx4 v[8:11], v192, s[12:13] offset:16
	global_load_dwordx4 v[12:15], v192, s[12:13]
	global_load_dwordx4 v[16:19], v192, s[10:11] offset:2064
	global_load_dwordx4 v[20:23], v192, s[10:11] offset:2048
	global_load_dwordx4 v[24:27], v192, s[12:13] offset:2064
	global_load_dwordx4 v[28:31], v192, s[12:13] offset:2048
	v_cndmask_b32_e32 v32, v229, v32, vcc
	v_lshlrev_b32_e32 v109, 2, v32
	v_xor_b32_e32 v32, 2, v229
	v_cmp_lt_i32_e32 vcc, v32, v231
	s_cmp_eq_u32 s28, 6
	s_cselect_b64 s[10:11], -1, 0
	v_cndmask_b32_e32 v32, v229, v32, vcc
	v_lshlrev_b32_e32 v121, 2, v32
	v_xor_b32_e32 v32, 4, v229
	v_cmp_lt_i32_e32 vcc, v32, v231
	s_and_b64 s[12:13], s[10:11], exec
	s_mov_b32 s12, 0x44d4000
	v_cndmask_b32_e32 v32, v229, v32, vcc
	v_lshlrev_b32_e32 v122, 2, v32
	v_xor_b32_e32 v32, 8, v229
	v_cmp_lt_i32_e32 vcc, v32, v231
	s_cselect_b32 s12, s12, 0x459a000
	s_or_b64 s[10:11], s[10:11], s[14:15]
	v_cndmask_b32_e32 v32, v229, v32, vcc
	v_lshlrev_b32_e32 v123, 2, v32
	v_xor_b32_e32 v32, 16, v229
	v_cmp_lt_i32_e32 vcc, v32, v231
	s_add_u32 s62, s4, 0x38260000
	s_addc_u32 s63, s5, 0
	v_cndmask_b32_e32 v32, v229, v32, vcc
	v_lshlrev_b32_e32 v124, 2, v32
	v_xor_b32_e32 v32, 32, v229
	s_add_u32 s64, s4, 0x3d2e4000
	v_cmp_lt_i32_e32 vcc, v32, v231
	s_addc_u32 s65, s5, 0
	s_add_u32 s14, s4, s12
	v_cndmask_b32_e32 v32, v229, v32, vcc
	v_lshlrev_b32_e32 v125, 2, v32
	v_lshlrev_b32_e32 v32, 4, v34
	s_addc_u32 s15, s5, 0
	v_lshl_add_u64 v[32:33], s[4:5], 0, v[32:33]
	s_mov_b64 s[4:5], 0x4660000
	v_lshl_add_u64 v[110:111], v[32:33], 0, s[4:5]
	v_cmp_eq_u32_e32 vcc, 0, v34
	s_mov_b64 s[4:5], 0x16660000
	v_lshlrev_b32_e32 v108, 3, v34
	s_mov_b32 s68, -1
	s_and_b64 s[12:13], s[6:7], vcc
	v_lshl_add_u64 v[112:113], s[14:15], 0, v[192:193]
	v_lshl_add_u64 v[114:115], v[32:33], 0, s[4:5]
	v_mov_b32_e32 v63, v62
	v_mov_b32_e32 v54, v62
	v_mov_b32_e32 v55, v62
	v_mov_b32_e32 v60, v62
	v_mov_b32_e32 v61, v62
	v_mov_b32_e32 v52, v62
	v_mov_b32_e32 v53, v62
	v_mov_b32_e32 v58, v62
	v_mov_b32_e32 v59, v62
	v_mov_b32_e32 v50, v62
	v_mov_b32_e32 v51, v62
	v_mov_b32_e32 v56, v62
	v_mov_b32_e32 v57, v62
	v_mov_b32_e32 v48, v62
	v_mov_b32_e32 v49, v62
	v_mov_b32_e32 v38, v62
	v_mov_b32_e32 v39, v62
	v_mov_b32_e32 v46, v62
	v_mov_b32_e32 v47, v62
	v_mov_b32_e32 v36, v62
	v_mov_b32_e32 v37, v62
	v_mov_b32_e32 v44, v62
	v_mov_b32_e32 v45, v62
	v_mov_b32_e32 v34, v62
	v_mov_b32_e32 v35, v62
	v_mov_b32_e32 v42, v62
	v_mov_b32_e32 v43, v62
	v_mov_b32_e32 v32, v62
	v_mov_b32_e32 v33, v62
	v_mov_b32_e32 v40, v62
	v_mov_b32_e32 v41, v62
	s_branch .LBB0_38
	s_nop 0
	s_nop 0
	s_nop 0
	s_nop 0
	s_nop 0
	s_nop 0
	s_nop 0
	s_nop 0
	s_nop 0
	s_nop 0
	s_nop 0
	s_nop 0
	s_nop 0
	s_nop 0
	s_nop 0
	s_nop 0
	s_nop 0
	s_nop 0
	s_nop 0
	s_nop 0
	s_nop 0
	s_nop 0
	s_nop 0
	s_nop 0
	s_nop 0
	s_nop 0
	s_nop 0
	s_nop 0
	s_nop 0
	s_nop 0
	s_nop 0
	s_nop 0
	s_nop 0
	s_nop 0
	s_nop 0
	s_nop 0
	s_nop 0
	s_nop 0
	s_nop 0
	s_nop 0
	s_nop 0
	s_nop 0
	s_nop 0
	s_nop 0
	s_nop 0
	s_nop 0
	s_nop 0
	s_nop 0
	s_nop 0
	s_nop 0
	s_nop 0
	s_nop 0
	s_nop 0
	s_nop 0
	s_nop 0
	s_nop 0
	s_nop 0
	s_nop 0
	s_nop 0
	s_nop 0
	s_nop 0
	s_nop 0
	s_nop 0
	s_nop 0
	s_nop 0
	s_nop 0
	s_nop 0
	s_nop 0
	s_nop 0

.LBB0_187:
	s_nop 0
	v_lshl_add_u64 v[8:9], v[40:41], 0, s[44:45]
	s_ashr_i32 s1, s0, 11
	s_and_b32 s4, s0, 0x7ff
	v_add_co_u32_e32 v10, vcc, s13, v8
	s_mul_hi_i32 s5, s1, 0x900
	s_mulk_i32 s1, 0x900
	s_addk_i32 s4, 0x100
	v_addc_co_u32_e32 v11, vcc, 0, v9, vcc
	s_add_u32 s4, s1, s4
	v_add_co_u32_e32 v8, vcc, s18, v8
	s_addc_u32 s5, s5, 0
	s_nop 0
	v_addc_co_u32_e32 v9, vcc, 0, v9, vcc
	global_load_dwordx4 v[48:51], v[10:11], off
	global_load_dwordx4 v[52:55], v[8:9], off
	s_mul_i32 s1, s5, 0xc00
	v_mad_u64_u32 v[8:9], s[6:7], s4, v238, v[36:37]
	v_add_u32_e32 v9, s1, v9
	global_load_dwordx4 v[56:59], v[8:9], off
	s_add_i32 s1, s0, 1
	v_lshl_add_u64 v[8:9], v[38:39], 0, s[44:45]
	s_ashr_i32 s6, s1, 11
	s_and_b32 s1, s1, 0x7ff
	v_add_co_u32_e32 v10, vcc, s13, v8
	s_mul_hi_i32 s7, s6, 0x900
	s_mulk_i32 s6, 0x900
	s_addk_i32 s1, 0x100
	v_addc_co_u32_e32 v11, vcc, 0, v9, vcc
	s_add_u32 s8, s6, s1
	v_add_co_u32_e32 v8, vcc, s18, v8
	s_addc_u32 s9, s7, 0
	s_nop 0
	v_addc_co_u32_e32 v9, vcc, 0, v9, vcc
	global_load_dwordx4 v[66:69], v[10:11], off
	global_load_dwordx4 v[70:73], v[8:9], off
	s_mul_i32 s1, s9, 0xc00
	v_mad_u64_u32 v[8:9], s[6:7], s8, v238, v[36:37]
	v_add_u32_e32 v9, s1, v9
	global_load_dwordx4 v[74:77], v[8:9], off
	s_add_i32 s6, s0, 2
	s_ashr_i32 s1, s6, 11
	s_and_b32 s7, s6, 0x7ff
	s_mul_hi_i32 s11, s1, 0x900
	s_mulk_i32 s1, 0x900
	s_addk_i32 s7, 0x100
	s_add_u32 s10, s1, s7
	s_addc_u32 s11, s11, 0
	s_ashr_i32 s7, s6, 31
	s_lshl_b64 s[6:7], s[6:7], 10
	v_lshl_add_u64 v[8:9], v[32:33], 0, s[6:7]
	global_load_dwordx4 v[20:23], v[8:9], off
	v_lshl_add_u64 v[8:9], v[34:35], 0, s[6:7]
	global_load_dwordx4 v[24:27], v[8:9], off
	s_mul_i32 s1, s11, 0xc00
	v_mad_u64_u32 v[8:9], s[6:7], s10, v238, v[36:37]
	v_add_u32_e32 v9, s1, v9
	global_load_dwordx4 v[28:31], v[8:9], off
	s_add_i32 s14, s0, 3
	s_ashr_i32 s1, s14, 11
	s_and_b32 s6, s14, 0x7ff
	s_mul_hi_i32 s7, s1, 0x900
	s_mulk_i32 s1, 0x900
	s_addk_i32 s6, 0x100
	s_add_u32 s6, s1, s6
	s_addc_u32 s7, s7, 0
	s_ashr_i32 s15, s14, 31
	s_lshl_b64 s[14:15], s[14:15], 10
	s_lshl_b64 s[4:5], s[4:5], 11
	s_add_u32 s4, s2, s4
	s_addc_u32 s5, s3, s5
	v_lshl_add_u64 v[12:13], v[34:35], 0, s[14:15]
	global_load_dwordx4 v[12:15], v[12:13], off
	v_lshl_add_u64 v[8:9], v[32:33], 0, s[14:15]
	s_mul_i32 s1, s7, 0xc00
	v_mad_u64_u32 v[16:17], s[14:15], s6, v238, v[36:37]
	v_add_u32_e32 v17, s1, v17
	global_load_dwordx4 v[8:11], v[8:9], off
	v_lshl_add_u64 v[38:39], v[38:39], 0, s[24:25]
	global_load_dwordx4 v[16:19], v[16:17], off
	v_lshl_add_u64 v[40:41], v[40:41], 0, s[24:25]
	s_waitcnt vmcnt(11)
	v_lshlrev_b32_e32 v42, 16, v51
	v_and_b32_e32 v43, 0xffff0000, v51
	s_waitcnt vmcnt(10)
	v_lshlrev_b32_e32 v44, 16, v55
	v_and_b32_e32 v45, 0xffff0000, v55
	v_pk_add_f32 v[42:43], v[42:43], v[44:45]
	s_waitcnt vmcnt(9)
	v_lshlrev_b32_e32 v46, 16, v59
	v_and_b32_e32 v47, 0xffff0000, v59
	v_mul_f32_e32 v51, 0xbfb8aa3b, v46
	v_mul_f32_e32 v44, 0xbfb8aa3b, v47
	v_exp_f32_e32 v51, v51
	v_exp_f32_e32 v44, v44
	v_add_f32_e32 v51, 1.0, v51
	v_add_f32_e32 v44, 1.0, v44
	v_rcp_f32_e32 v78, v51
	v_rcp_f32_e32 v79, v44
	v_and_b32_e32 v51, 0xffff0000, v58
	v_pk_mul_f32 v[44:45], v[78:79], v[46:47]
	s_nop 0
	v_pk_mul_f32 v[42:43], v[42:43], v[44:45]
	v_lshlrev_b32_e32 v44, 16, v50
	v_and_b32_e32 v45, 0xffff0000, v50
	v_lshlrev_b32_e32 v46, 16, v54
	v_and_b32_e32 v47, 0xffff0000, v54
	v_lshlrev_b32_e32 v50, 16, v58
	v_mul_f32_e32 v54, 0xbfb8aa3b, v50
	v_pk_add_f32 v[44:45], v[44:45], v[46:47]
	v_mul_f32_e32 v46, 0xbfb8aa3b, v51
	v_exp_f32_e32 v54, v54
	v_exp_f32_e32 v46, v46
	v_pk_mul_f32 v[78:79], v[42:43], v[42:43]
	v_add_f32_e32 v54, 1.0, v54
	v_add_f32_e32 v46, 1.0, v46
	v_rcp_f32_e32 v54, v54
	v_rcp_f32_e32 v55, v46
	s_nop 0
	v_pk_mul_f32 v[46:47], v[54:55], v[50:51]
	v_lshlrev_b32_e32 v54, 16, v57
	v_pk_mul_f32 v[44:45], v[44:45], v[46:47]
	v_lshlrev_b32_e32 v46, 16, v49
	v_and_b32_e32 v47, 0xffff0000, v49
	v_mul_f32_e32 v49, 0xbfb8aa3b, v54
	v_exp_f32_e32 v49, v49
	v_and_b32_e32 v55, 0xffff0000, v57
	v_lshlrev_b32_e32 v50, 16, v53
	v_and_b32_e32 v51, 0xffff0000, v53
	v_add_f32_e32 v49, 1.0, v49
	v_rcp_f32_e32 v58, v49
	v_mul_f32_e32 v49, 0xbfb8aa3b, v55
	v_exp_f32_e32 v49, v49
	v_pk_add_f32 v[46:47], v[46:47], v[50:51]
	v_and_b32_e32 v53, 0xffff0000, v56
	s_waitcnt vmcnt(6)
	v_and_b32_e32 v57, 0xffff0000, v77
	v_add_f32_e32 v49, 1.0, v49
	v_rcp_f32_e32 v59, v49
	v_and_b32_e32 v49, 0xffff0000, v52
	v_pk_mul_f32 v[80:81], v[44:45], v[44:45]
	v_pk_mul_f32 v[50:51], v[58:59], v[54:55]
	s_nop 0
	v_pk_mul_f32 v[46:47], v[46:47], v[50:51]
	v_lshlrev_b32_e32 v50, 16, v48
	v_and_b32_e32 v51, 0xffff0000, v48
	v_lshlrev_b32_e32 v48, 16, v52
	v_lshlrev_b32_e32 v52, 16, v56
	v_mul_f32_e32 v54, 0xbfb8aa3b, v52
	v_pk_add_f32 v[48:49], v[50:51], v[48:49]
	v_mul_f32_e32 v50, 0xbfb8aa3b, v53
	v_exp_f32_e32 v54, v54
	v_exp_f32_e32 v50, v50
	v_lshlrev_b32_e32 v56, 16, v77
	v_mul_f32_e32 v58, 0xbfb8aa3b, v56
	v_add_f32_e32 v54, 1.0, v54
	v_add_f32_e32 v50, 1.0, v50
	v_rcp_f32_e32 v54, v54
	v_rcp_f32_e32 v55, v50
	v_exp_f32_e32 v58, v58
	v_pk_mul_f32 v[50:51], v[54:55], v[52:53]
	s_nop 0
	v_pk_mul_f32 v[52:53], v[48:49], v[50:51]
	v_lshlrev_b32_e32 v50, 16, v69
	v_and_b32_e32 v51, 0xffff0000, v69
	v_lshlrev_b32_e32 v54, 16, v73
	v_and_b32_e32 v55, 0xffff0000, v73
	v_pk_add_f32 v[50:51], v[50:51], v[54:55]
	v_mul_f32_e32 v54, 0xbfb8aa3b, v57
	v_exp_f32_e32 v54, v54
	v_add_f32_e32 v58, 1.0, v58
	v_rcp_f32_e32 v58, v58
	v_and_b32_e32 v73, 0xffff0000, v75
	v_add_f32_e32 v54, 1.0, v54
	v_rcp_f32_e32 v59, v54
	v_lshl_add_u64 v[48:49], s[4:5], 0, v[192:193]
	s_mov_b32 s4, 0x358637bd
	v_pk_mul_f32 v[54:55], v[58:59], v[56:57]
	s_nop 0
	v_pk_mul_f32 v[50:51], v[50:51], v[54:55]
	v_lshlrev_b32_e32 v54, 16, v68
	v_and_b32_e32 v55, 0xffff0000, v68
	v_lshlrev_b32_e32 v56, 16, v72
	v_and_b32_e32 v57, 0xffff0000, v72
	v_lshlrev_b32_e32 v58, 16, v76
	v_and_b32_e32 v59, 0xffff0000, v76
	v_mul_f32_e32 v68, 0xbfb8aa3b, v58
	v_pk_add_f32 v[54:55], v[54:55], v[56:57]
	v_mul_f32_e32 v56, 0xbfb8aa3b, v59
	v_exp_f32_e32 v68, v68
	v_exp_f32_e32 v56, v56
	v_lshlrev_b32_e32 v72, 16, v75
	v_mov_b32_e32 v75, v53
	v_add_f32_e32 v68, 1.0, v68
	v_add_f32_e32 v56, 1.0, v56
	v_rcp_f32_e32 v68, v68
	v_rcp_f32_e32 v69, v56
	v_pk_mul_f32 v[82:83], v[50:51], v[50:51]
	v_pk_mul_f32 v[56:57], v[68:69], v[58:59]
	s_nop 0
	v_pk_mul_f32 v[54:55], v[54:55], v[56:57]
	v_lshlrev_b32_e32 v56, 16, v67
	v_and_b32_e32 v57, 0xffff0000, v67
	v_lshlrev_b32_e32 v58, 16, v71
	v_and_b32_e32 v59, 0xffff0000, v71
	v_mul_f32_e32 v67, 0xbfb8aa3b, v72
	v_pk_add_f32 v[56:57], v[56:57], v[58:59]
	v_mul_f32_e32 v58, 0xbfb8aa3b, v73
	v_exp_f32_e32 v67, v67
	v_exp_f32_e32 v58, v58
	v_and_b32_e32 v71, 0xffff0000, v74
	v_pk_mul_f32 v[68:69], v[54:55], v[54:55]
	v_add_f32_e32 v67, 1.0, v67
	v_add_f32_e32 v58, 1.0, v58
	v_rcp_f32_e32 v76, v67
	v_rcp_f32_e32 v77, v58
	v_and_b32_e32 v67, 0xffff0000, v70
	v_pk_mul_f32 v[58:59], v[76:77], v[72:73]
	s_nop 0
	v_pk_mul_f32 v[56:57], v[56:57], v[58:59]
	v_lshlrev_b32_e32 v58, 16, v66
	v_and_b32_e32 v59, 0xffff0000, v66
	v_lshlrev_b32_e32 v66, 16, v70
	v_lshlrev_b32_e32 v70, 16, v74
	v_mul_f32_e32 v72, 0xbfb8aa3b, v70
	v_pk_add_f32 v[58:59], v[58:59], v[66:67]
	v_mul_f32_e32 v66, 0xbfb8aa3b, v71
	v_exp_f32_e32 v72, v72
	v_exp_f32_e32 v66, v66
	v_add_f32_e32 v72, 1.0, v72
	v_add_f32_e32 v66, 1.0, v66
	v_rcp_f32_e32 v72, v72
	v_rcp_f32_e32 v73, v66
	s_nop 0
	v_pk_mul_f32 v[66:67], v[72:73], v[70:71]
	s_nop 0
	v_pk_mul_f32 v[58:59], v[58:59], v[66:67]
	v_mov_b32_e32 v73, v52
	v_mov_b32_e32 v74, v59
	v_mov_b32_e32 v72, v58
	v_pk_mul_f32 v[74:75], v[74:75], v[74:75]
	v_mov_b32_e32 v66, v56
	v_mov_b32_e32 v67, v46
	v_pk_fma_f32 v[72:73], v[72:73], v[72:73], v[74:75]
	v_mov_b32_e32 v70, v57
	v_mov_b32_e32 v71, v47
	v_pk_fma_f32 v[66:67], v[66:67], v[66:67], v[72:73]
	s_nop 0
	v_pk_fma_f32 v[66:67], v[70:71], v[70:71], v[66:67]
	v_mov_b32_e32 v70, v68
	v_mov_b32_e32 v71, v80
	v_pk_add_f32 v[66:67], v[70:71], v[66:67]
	v_mov_b32_e32 v80, v69
	v_pk_add_f32 v[66:67], v[80:81], v[66:67]
	v_mov_b32_e32 v68, v82
	v_mov_b32_e32 v69, v78
	v_pk_add_f32 v[66:67], v[68:69], v[66:67]
	v_mov_b32_e32 v78, v83
	v_pk_add_f32 v[66:67], v[78:79], v[66:67]
	s_nop 1
	v_add_f32_dpp v66, v66, v66 quad_perm:[1,0,3,2] row_mask:0xf bank_mask:0xf
	v_add_f32_dpp v67, v67, v67 quad_perm:[1,0,3,2] row_mask:0xf bank_mask:0xf
	s_nop 1
	v_add_f32_dpp v66, v66, v66 quad_perm:[2,3,0,1] row_mask:0xf bank_mask:0xf
	v_add_f32_dpp v67, v67, v67 quad_perm:[2,3,0,1] row_mask:0xf bank_mask:0xf
	s_nop 1
	v_add_f32_dpp v66, v66, v66 row_half_mirror row_mask:0xf bank_mask:0xf
	v_add_f32_dpp v67, v67, v67 row_half_mirror row_mask:0xf bank_mask:0xf
	s_nop 1
	v_add_f32_dpp v66, v66, v66 row_mirror row_mask:0xf bank_mask:0xf
	v_add_f32_dpp v67, v67, v67 row_mirror row_mask:0xf bank_mask:0xf
	v_mov_b32_e32 v68, v66
	v_mov_b32_e32 v69, v67
	s_nop 1
	v_permlane16_swap_b32_e32 v68, v66
	v_permlane16_swap_b32_e32 v69, v67
	v_pk_add_f32 v[66:67], v[66:67], v[68:69]
	v_mov_b32_e32 v68, v66
	v_mov_b32_e32 v69, v67
	s_nop 1
	v_permlane32_swap_b32_e32 v68, v66
	v_permlane32_swap_b32_e32 v69, v67
	v_pk_add_f32 v[66:67], v[66:67], v[68:69]
	v_mov_b64_e32 v[68:69], s[4:5]
	v_pk_fma_f32 v[66:67], v[66:67], s[22:23], v[68:69] op_sel_hi:[1,0,0]
	s_nop 0
	v_mul_f32_e32 v70, 0x4b800000, v67
	v_cmp_gt_f32_e64 s[4:5], s19, v67
	v_cmp_gt_f32_e32 vcc, s19, v66
	s_nop 0
	v_cndmask_b32_e64 v67, v67, v70, s[4:5]
	v_rsq_f32_e32 v67, v67
	s_nop 0
	v_mul_f32_e32 v70, 0x45800000, v67
	v_cndmask_b32_e64 v70, v67, v70, s[4:5]
	v_pk_mul_f32 v[46:47], v[46:47], v[70:71] op_sel_hi:[1,0]
	v_pk_mul_f32 v[52:53], v[52:53], v[70:71] op_sel_hi:[1,0]
	v_pk_mul_f32 v[46:47], v[6:7], v[46:47]
	v_pk_mul_f32 v[44:45], v[44:45], v[70:71] op_sel_hi:[1,0]
	v_pk_mul_f32 v[42:43], v[42:43], v[70:71] op_sel_hi:[1,0]
	v_pk_mul_f32 v[52:53], v[4:5], v[52:53]
	v_pk_mul_f32 v[44:45], v[0:1], v[44:45]
	v_pk_mul_f32 v[70:71], v[2:3], v[42:43]
	v_cvt_pk_bf16_f32 v43, v46, v47
	v_add_co_u32_e64 v46, s[4:5], s20, v48
	v_cvt_pk_bf16_f32 v42, v52, v53
	v_cvt_pk_bf16_f32 v44, v44, v45
	v_cvt_pk_bf16_f32 v45, v70, v71
	v_addc_co_u32_e64 v47, s[4:5], 0, v49, s[4:5]
	global_store_dwordx4 v[46:47], v[42:45], off offset:1024
	s_lshl_b64 s[4:5], s[8:9], 11
	s_add_u32 s4, s2, s4
	v_mul_f32_e32 v42, 0x4b800000, v66
	v_cndmask_b32_e32 v42, v66, v42, vcc
	v_rsq_f32_e32 v42, v42
	s_addc_u32 s5, s3, s5
	v_mul_f32_e32 v43, 0x45800000, v42
	v_cndmask_b32_e32 v42, v42, v43, vcc
	v_pk_mul_f32 v[46:47], v[56:57], v[42:43] op_sel_hi:[1,0]
	v_pk_mul_f32 v[44:45], v[58:59], v[42:43] op_sel_hi:[1,0]
	v_pk_mul_f32 v[46:47], v[6:7], v[46:47]
	v_pk_mul_f32 v[48:49], v[54:55], v[42:43] op_sel_hi:[1,0]
	v_pk_mul_f32 v[42:43], v[50:51], v[42:43] op_sel_hi:[1,0]
	v_pk_mul_f32 v[44:45], v[4:5], v[44:45]
	v_pk_mul_f32 v[50:51], v[2:3], v[42:43]
	v_cvt_pk_bf16_f32 v43, v46, v47
	v_lshl_add_u64 v[46:47], s[4:5], 0, v[192:193]
	v_pk_mul_f32 v[48:49], v[0:1], v[48:49]
	v_add_co_u32_e32 v46, vcc, s20, v46
	v_cvt_pk_bf16_f32 v42, v44, v45
	v_cvt_pk_bf16_f32 v44, v48, v49
	v_cvt_pk_bf16_f32 v45, v50, v51
	v_addc_co_u32_e32 v47, vcc, 0, v47, vcc
	global_store_dwordx4 v[46:47], v[42:45], off offset:1024
	s_waitcnt vmcnt(5)
	v_lshlrev_b32_e32 v46, 16, v31
	v_and_b32_e32 v47, 0xffff0000, v31
	v_lshlrev_b32_e32 v42, 16, v23
	v_and_b32_e32 v43, 0xffff0000, v23
	v_mul_f32_e32 v23, 0xbfb8aa3b, v46
	v_exp_f32_e32 v23, v23
	v_lshlrev_b32_e32 v44, 16, v27
	v_and_b32_e32 v45, 0xffff0000, v27
	v_pk_add_f32 v[42:43], v[42:43], v[44:45]
	v_add_f32_e32 v23, 1.0, v23
	v_rcp_f32_e32 v48, v23
	v_mul_f32_e32 v23, 0xbfb8aa3b, v47
	v_exp_f32_e32 v23, v23
	v_and_b32_e32 v27, 0xffff0000, v30
	v_mul_f32_e32 v31, 0xbfb8aa3b, v27
	v_exp_f32_e32 v31, v31
	v_add_f32_e32 v23, 1.0, v23
	v_rcp_f32_e32 v49, v23
	v_and_b32_e32 v23, 0xffff0000, v26
	v_add_f32_e32 v31, 1.0, v31
	v_rcp_f32_e32 v31, v31
	v_pk_mul_f32 v[44:45], v[48:49], v[46:47]
	v_lshlrev_b32_e32 v46, 16, v22
	v_and_b32_e32 v47, 0xffff0000, v22
	v_lshlrev_b32_e32 v22, 16, v26
	v_lshlrev_b32_e32 v26, 16, v30
	v_mul_f32_e32 v30, 0xbfb8aa3b, v26
	v_exp_f32_e32 v30, v30
	v_lshlrev_b32_e32 v48, 16, v29
	v_and_b32_e32 v49, 0xffff0000, v29
	v_pk_add_f32 v[22:23], v[46:47], v[22:23]
	v_add_f32_e32 v30, 1.0, v30
	v_rcp_f32_e32 v30, v30
	v_lshlrev_b32_e32 v46, 16, v25
	v_and_b32_e32 v47, 0xffff0000, v25
	v_and_b32_e32 v25, 0xffff0000, v28
	v_pk_mul_f32 v[26:27], v[30:31], v[26:27]
	v_lshlrev_b32_e32 v30, 16, v21
	v_and_b32_e32 v31, 0xffff0000, v21
	v_mul_f32_e32 v21, 0xbfb8aa3b, v48
	v_exp_f32_e32 v21, v21
	v_pk_add_f32 v[30:31], v[30:31], v[46:47]
	v_mul_f32_e32 v29, 0xbfb8aa3b, v25
	v_exp_f32_e32 v29, v29
	v_add_f32_e32 v21, 1.0, v21
	v_rcp_f32_e32 v50, v21
	v_mul_f32_e32 v21, 0xbfb8aa3b, v49
	v_exp_f32_e32 v21, v21
	v_add_f32_e32 v29, 1.0, v29
	v_rcp_f32_e32 v29, v29
	v_pk_mul_f32 v[22:23], v[22:23], v[26:27]
	v_add_f32_e32 v21, 1.0, v21
	v_rcp_f32_e32 v51, v21
	v_and_b32_e32 v21, 0xffff0000, v24
	v_pk_mul_f32 v[26:27], v[22:23], v[22:23]
	v_pk_mul_f32 v[42:43], v[42:43], v[44:45]
	v_pk_mul_f32 v[46:47], v[50:51], v[48:49]
	s_waitcnt vmcnt(2)
	v_lshlrev_b32_e32 v48, 16, v19
	v_pk_mul_f32 v[30:31], v[30:31], v[46:47]
	v_lshlrev_b32_e32 v46, 16, v20
	v_and_b32_e32 v47, 0xffff0000, v20
	v_lshlrev_b32_e32 v20, 16, v24
	v_lshlrev_b32_e32 v24, 16, v28
	v_mul_f32_e32 v28, 0xbfb8aa3b, v24
	v_exp_f32_e32 v28, v28
	v_and_b32_e32 v49, 0xffff0000, v19
	v_pk_add_f32 v[20:21], v[46:47], v[20:21]
	v_lshlrev_b32_e32 v46, 16, v15
	v_add_f32_e32 v28, 1.0, v28
	v_rcp_f32_e32 v28, v28
	v_and_b32_e32 v47, 0xffff0000, v15
	v_and_b32_e32 v15, 0xffff0000, v18
	v_mul_f32_e32 v19, 0xbfb8aa3b, v15
	v_pk_mul_f32 v[24:25], v[28:29], v[24:25]
	v_lshlrev_b32_e32 v28, 16, v11
	v_and_b32_e32 v29, 0xffff0000, v11
	v_mul_f32_e32 v11, 0xbfb8aa3b, v48
	v_exp_f32_e32 v11, v11
	v_pk_add_f32 v[28:29], v[28:29], v[46:47]
	v_exp_f32_e32 v19, v19
	v_pk_mul_f32 v[20:21], v[20:21], v[24:25]
	v_add_f32_e32 v11, 1.0, v11
	v_rcp_f32_e32 v50, v11
	v_mul_f32_e32 v11, 0xbfb8aa3b, v49
	v_exp_f32_e32 v11, v11
	v_add_f32_e32 v19, 1.0, v19
	v_rcp_f32_e32 v19, v19
	v_pk_mul_f32 v[44:45], v[42:43], v[42:43]
	v_add_f32_e32 v11, 1.0, v11
	v_rcp_f32_e32 v51, v11
	v_and_b32_e32 v11, 0xffff0000, v14
	s_lshl_b64 s[4:5], s[10:11], 11
	s_add_u32 s4, s2, s4
	v_pk_mul_f32 v[46:47], v[50:51], v[48:49]
	v_lshlrev_b32_e32 v48, 16, v10
	v_and_b32_e32 v49, 0xffff0000, v10
	v_lshlrev_b32_e32 v10, 16, v14
	v_lshlrev_b32_e32 v14, 16, v18
	v_mul_f32_e32 v18, 0xbfb8aa3b, v14
	v_exp_f32_e32 v18, v18
	v_lshlrev_b32_e32 v50, 16, v17
	v_and_b32_e32 v51, 0xffff0000, v17
	v_pk_add_f32 v[10:11], v[48:49], v[10:11]
	v_add_f32_e32 v18, 1.0, v18
	v_rcp_f32_e32 v18, v18
	v_lshlrev_b32_e32 v48, 16, v13
	v_and_b32_e32 v49, 0xffff0000, v13
	v_and_b32_e32 v13, 0xffff0000, v16
	v_pk_mul_f32 v[14:15], v[18:19], v[14:15]
	v_lshlrev_b32_e32 v18, 16, v9
	v_and_b32_e32 v19, 0xffff0000, v9
	v_mul_f32_e32 v9, 0xbfb8aa3b, v50
	v_exp_f32_e32 v9, v9
	v_pk_add_f32 v[18:19], v[18:19], v[48:49]
	v_mul_f32_e32 v17, 0xbfb8aa3b, v13
	v_exp_f32_e32 v17, v17
	v_add_f32_e32 v9, 1.0, v9
	v_rcp_f32_e32 v52, v9
	v_mul_f32_e32 v9, 0xbfb8aa3b, v51
	v_exp_f32_e32 v9, v9
	v_add_f32_e32 v17, 1.0, v17
	v_rcp_f32_e32 v17, v17
	v_pk_mul_f32 v[14:15], v[10:11], v[14:15]
	v_add_f32_e32 v9, 1.0, v9
	v_rcp_f32_e32 v53, v9
	v_and_b32_e32 v9, 0xffff0000, v12
	v_pk_mul_f32 v[10:11], v[14:15], v[14:15]
	v_pk_mul_f32 v[28:29], v[28:29], v[46:47]
	v_pk_mul_f32 v[48:49], v[52:53], v[50:51]
	v_mov_b32_e32 v51, v21
	v_pk_mul_f32 v[18:19], v[18:19], v[48:49]
	v_lshlrev_b32_e32 v48, 16, v8
	v_and_b32_e32 v49, 0xffff0000, v8
	v_lshlrev_b32_e32 v8, 16, v12
	v_lshlrev_b32_e32 v12, 16, v16
	v_mul_f32_e32 v16, 0xbfb8aa3b, v12
	v_exp_f32_e32 v16, v16
	v_pk_add_f32 v[8:9], v[48:49], v[8:9]
	v_mov_b32_e32 v49, v20
	v_pk_mul_f32 v[46:47], v[28:29], v[28:29]
	v_add_f32_e32 v16, 1.0, v16
	v_rcp_f32_e32 v16, v16
	s_addc_u32 s5, s3, s5
	v_lshl_add_u64 v[24:25], s[4:5], 0, v[192:193]
	v_pk_mul_f32 v[12:13], v[16:17], v[12:13]
	s_nop 0
	v_pk_mul_f32 v[12:13], v[8:9], v[12:13]
	v_mov_b32_e32 v8, v18
	v_mov_b32_e32 v50, v13
	v_mov_b32_e32 v48, v12
	v_pk_mul_f32 v[50:51], v[50:51], v[50:51]
	v_mov_b32_e32 v9, v30
	v_pk_fma_f32 v[48:49], v[48:49], v[48:49], v[50:51]
	v_mov_b32_e32 v16, v19
	v_mov_b32_e32 v17, v31
	v_pk_fma_f32 v[8:9], v[8:9], v[8:9], v[48:49]
	s_nop 0
	v_pk_fma_f32 v[8:9], v[16:17], v[16:17], v[8:9]
	v_mov_b32_e32 v16, v10
	v_mov_b32_e32 v17, v26
	v_pk_add_f32 v[8:9], v[16:17], v[8:9]
	v_mov_b32_e32 v26, v11
	v_pk_add_f32 v[8:9], v[26:27], v[8:9]
	v_mov_b32_e32 v10, v46
	v_mov_b32_e32 v11, v44
	v_pk_add_f32 v[8:9], v[10:11], v[8:9]
	v_mov_b32_e32 v44, v47
	v_pk_add_f32 v[8:9], v[44:45], v[8:9]
	s_nop 1
	v_add_f32_dpp v8, v8, v8 quad_perm:[1,0,3,2] row_mask:0xf bank_mask:0xf
	v_add_f32_dpp v9, v9, v9 quad_perm:[1,0,3,2] row_mask:0xf bank_mask:0xf
	s_nop 1
	v_add_f32_dpp v8, v8, v8 quad_perm:[2,3,0,1] row_mask:0xf bank_mask:0xf
	v_add_f32_dpp v9, v9, v9 quad_perm:[2,3,0,1] row_mask:0xf bank_mask:0xf
	s_nop 1
	v_add_f32_dpp v8, v8, v8 row_half_mirror row_mask:0xf bank_mask:0xf
	v_add_f32_dpp v9, v9, v9 row_half_mirror row_mask:0xf bank_mask:0xf
	s_nop 1
	v_add_f32_dpp v8, v8, v8 row_mirror row_mask:0xf bank_mask:0xf
	v_add_f32_dpp v9, v9, v9 row_mirror row_mask:0xf bank_mask:0xf
	v_mov_b32_e32 v10, v8
	v_mov_b32_e32 v11, v9
	s_nop 1
	v_permlane16_swap_b32_e32 v10, v8
	v_permlane16_swap_b32_e32 v11, v9
	v_pk_add_f32 v[8:9], v[8:9], v[10:11]
	v_mov_b32_e32 v10, v8
	v_mov_b32_e32 v11, v9
	s_nop 1
	v_permlane32_swap_b32_e32 v10, v8
	v_permlane32_swap_b32_e32 v11, v9
	v_pk_add_f32 v[8:9], v[8:9], v[10:11]
	s_nop 0
	v_pk_fma_f32 v[16:17], v[8:9], s[22:23], v[68:69] op_sel_hi:[1,0,0]
	s_nop 0
	v_mul_f32_e32 v8, 0x4b800000, v17
	v_cmp_gt_f32_e64 s[4:5], s19, v17
	v_cmp_gt_f32_e32 vcc, s19, v16
	s_nop 0
	v_cndmask_b32_e64 v8, v17, v8, s[4:5]
	v_rsq_f32_e32 v8, v8
	s_nop 0
	v_mul_f32_e32 v9, 0x45800000, v8
	v_cndmask_b32_e64 v8, v8, v9, s[4:5]
	v_pk_mul_f32 v[10:11], v[20:21], v[8:9] op_sel_hi:[1,0]
	v_pk_mul_f32 v[20:21], v[30:31], v[8:9] op_sel_hi:[1,0]
	v_pk_mul_f32 v[22:23], v[22:23], v[8:9] op_sel_hi:[1,0]
	v_pk_mul_f32 v[20:21], v[6:7], v[20:21]
	v_pk_mul_f32 v[8:9], v[42:43], v[8:9] op_sel_hi:[1,0]
	v_pk_mul_f32 v[10:11], v[4:5], v[10:11]
	v_pk_mul_f32 v[22:23], v[0:1], v[22:23]
	v_pk_mul_f32 v[26:27], v[2:3], v[8:9]
	v_cvt_pk_bf16_f32 v9, v20, v21
	v_add_co_u32_e64 v20, s[4:5], s20, v24
	v_cvt_pk_bf16_f32 v8, v10, v11
	v_cvt_pk_bf16_f32 v10, v22, v23
	v_cvt_pk_bf16_f32 v11, v26, v27
	v_addc_co_u32_e64 v21, s[4:5], 0, v25, s[4:5]
	global_store_dwordx4 v[20:21], v[8:11], off offset:1024
	s_lshl_b64 s[4:5], s[6:7], 11
	s_add_u32 s4, s2, s4
	v_mul_f32_e32 v8, 0x4b800000, v16
	v_cndmask_b32_e32 v8, v16, v8, vcc
	v_rsq_f32_e32 v8, v8
	s_addc_u32 s5, s3, s5
	s_add_i32 s0, s0, 4
	s_cmp_ge_i32 s0, s12
	v_mul_f32_e32 v9, 0x45800000, v8
	v_cndmask_b32_e32 v8, v8, v9, vcc
	v_pk_mul_f32 v[10:11], v[12:13], v[8:9] op_sel_hi:[1,0]
	v_pk_mul_f32 v[12:13], v[18:19], v[8:9] op_sel_hi:[1,0]
	v_pk_mul_f32 v[14:15], v[14:15], v[8:9] op_sel_hi:[1,0]
	v_pk_mul_f32 v[12:13], v[6:7], v[12:13]
	v_pk_mul_f32 v[8:9], v[28:29], v[8:9] op_sel_hi:[1,0]
	v_pk_mul_f32 v[10:11], v[4:5], v[10:11]
	v_pk_mul_f32 v[16:17], v[2:3], v[8:9]
	v_cvt_pk_bf16_f32 v9, v12, v13
	v_lshl_add_u64 v[12:13], s[4:5], 0, v[192:193]
	v_pk_mul_f32 v[14:15], v[0:1], v[14:15]
	v_add_co_u32_e32 v12, vcc, 0x16660000, v12
	v_cvt_pk_bf16_f32 v8, v10, v11
	v_cvt_pk_bf16_f32 v10, v14, v15
	v_cvt_pk_bf16_f32 v11, v16, v17
	v_addc_co_u32_e32 v13, vcc, 0, v13, vcc
	global_store_dwordx4 v[12:13], v[8:11], off offset:1024
	s_cbranch_scc0 .LBB0_187

.LBB0_470:
	v_or_b32_e32 v0, s21, v3
	s_cmp_lt_i32 s28, 0
	v_cmp_le_i32_e32 vcc, s23, v0
	s_cselect_b64 s[4:5], -1, 0
	s_waitcnt lgkmcnt(0)
	s_barrier
	v_add_u32_e32 v1, s28, v3
	v_add_u32_e32 v0, s24, v0
	s_mul_i32 s27, s27, s25
	v_cndmask_b32_e64 v0, v1, v0, s[4:5]
	s_sub_i32 s12, s22, s27
	v_ashrrev_i32_e32 v1, 31, v0
	s_lshl_b32 s12, s12, 6
	v_lshl_add_u64 v[0:1], v[0:1], 2, s[10:11]
	v_mov_b32_e32 v20, 0
	v_mov_b32_e32 v21, 0
	v_mov_b32_e32 v22, 0
	v_mov_b32_e32 v23, 0
	v_mov_b32_e32 v24, 0
	v_mov_b32_e32 v25, 0
	v_mov_b32_e32 v26, 0
	v_mov_b32_e32 v27, 0
	s_mov_b64 s[18:19], exec
	s_andn2_b64 exec, exec, vcc
	s_cbranch_execz .Lcvt_join
	v_add_u32_e32 v80, s12, v2
	v_ashrrev_i32_e32 v81, 31, v80
	v_mul_lo_u32 v81, s8, v81
	v_mul_lo_u32 v84, s9, v80
	v_mad_u64_u32 v[82:83], s[4:5], s8, v80, 0
	v_add3_u32 v83, v83, v81, v84
	v_lshl_add_u64 v[82:83], v[82:83], 2, v[0:1]
	global_load_dword v21, v[82:83], off
	v_add_u32_e32 v86, 8, v80
	v_ashrrev_i32_e32 v87, 31, v86
	v_mul_lo_u32 v87, s8, v87
	v_mul_lo_u32 v90, s9, v86
	v_mad_u64_u32 v[88:89], s[4:5], s8, v86, 0
	v_add3_u32 v89, v89, v87, v90
	v_lshl_add_u64 v[88:89], v[88:89], 2, v[0:1]
	global_load_dword v22, v[88:89], off
	v_add_u32_e32 v92, s12, v6
	v_ashrrev_i32_e32 v93, 31, v92
	v_mul_lo_u32 v93, s8, v93
	v_mul_lo_u32 v96, s9, v92
	v_mad_u64_u32 v[94:95], s[4:5], s8, v92, 0
	v_add3_u32 v95, v95, v93, v96
	v_lshl_add_u64 v[94:95], v[94:95], 2, v[0:1]
	global_load_dword v23, v[94:95], off
	v_add_u32_e32 v98, s12, v8
	v_ashrrev_i32_e32 v99, 31, v98
	v_mul_lo_u32 v99, s8, v99
	v_mul_lo_u32 v102, s9, v98
	v_mad_u64_u32 v[100:101], s[4:5], s8, v98, 0
	v_add3_u32 v101, v101, v99, v102
	v_lshl_add_u64 v[100:101], v[100:101], 2, v[0:1]
	global_load_dword v24, v[100:101], off
	v_add_u32_e32 v104, s12, v10
	v_ashrrev_i32_e32 v105, 31, v104
	v_mul_lo_u32 v105, s8, v105
	v_mul_lo_u32 v108, s9, v104
	v_mad_u64_u32 v[106:107], s[4:5], s8, v104, 0
	v_add3_u32 v107, v107, v105, v108
	v_lshl_add_u64 v[106:107], v[106:107], 2, v[0:1]
	global_load_dword v25, v[106:107], off
	v_add_u32_e32 v110, s12, v12
	v_ashrrev_i32_e32 v111, 31, v110
	v_mul_lo_u32 v111, s8, v111
	v_mul_lo_u32 v114, s9, v110
	v_mad_u64_u32 v[112:113], s[4:5], s8, v110, 0
	v_add3_u32 v113, v113, v111, v114
	v_lshl_add_u64 v[112:113], v[112:113], 2, v[0:1]
	global_load_dword v26, v[112:113], off
	v_add_u32_e32 v116, s12, v14
	v_ashrrev_i32_e32 v117, 31, v116
	v_mul_lo_u32 v117, s8, v117
	v_mul_lo_u32 v120, s9, v116
	v_mad_u64_u32 v[118:119], s[4:5], s8, v116, 0
	v_add3_u32 v119, v119, v117, v120
	v_lshl_add_u64 v[118:119], v[118:119], 2, v[0:1]
	global_load_dword v27, v[118:119], off
	v_add_u32_e32 v122, s12, v16
	v_ashrrev_i32_e32 v123, 31, v122
	v_mul_lo_u32 v123, s8, v123
	v_mul_lo_u32 v126, s9, v122
	v_mad_u64_u32 v[124:125], s[4:5], s8, v122, 0
	v_add3_u32 v125, v125, v123, v126
	v_lshl_add_u64 v[124:125], v[124:125], 2, v[0:1]
	global_load_dword v20, v[124:125], off
.Lcvt_join:
	s_mov_b64 exec, s[18:19]
	s_mov_b64 s[4:5], exec
	s_waitcnt vmcnt(0)
	ds_write_b32 v4, v21
	ds_write_b32 v5, v22
	ds_write_b32 v7, v23
	ds_write_b32 v9, v24
	ds_write_b32 v11, v25
	ds_write_b32 v13, v26
	ds_write_b32 v15, v27
	s_branch .LBB0_438
	s_nop 0
	s_nop 0
